# adds: NSA/fox unit epilogues issue their 8 gate loads up front (counted vmcnt) instead of 8 serialized load-wait-store steps
# speedup vs baseline: 1.3395x; 1.0014x over previous
; __device__ __forceinline__ unsigned pk2(float lo, float hi) { f32x2_t v = {lo, hi}; bf16x2_t b = __builtin_convertvector(v, bf16x2_t); return __builtin_bit_cast(unsigned, b); }
; __device__ __forceinline__ float lo16(unsigned w) { return __uint_as_float(w << 16); }
; __device__ __forceinline__ float hi16(unsigned w) { return __uint_as_float(w & 0xffff0000u); }
; __device__ __forceinline__ float frcp(float x) { return __builtin_amdgcn_rcpf(x); }
; __device__ __forceinline__ float siluf_(float x) { return x * sigmoidf_(x); }
; __device__ __forceinline__ float merge_l(float l) { return l + __shfl_xor(l, 32); }
; __device__ __forceinline__ void nsa_unit(int b, int qt, const bf16_t* proj, const bf16_t* vt, const bf16_t* kc, const bf16_t* vcT, bf16_t* ab0, LAS unsigned char* lds, int tid, int wid, int lane) {
;     ...
;     const float sc = g2 * frcp(merge_l(st.l));
; #pragma unroll
;     for (int r = 0; r < 16; ++r) { ot[0][r] = stash[r * 64] + sc * st.o[0][r]; ot[1][r] = stash[(16 + r) * 64] + sc * st.o[1][r]; }
;   }
;   const bf16_t* gp = proj + tok * NP + C_GATE + head * 64;
;   bf16_t* op = ab0 + tok * 256 + head * 64;
; #pragma unroll
;   for (int dh = 0; dh < 2; ++dh)
; #pragma unroll
;     for (int g = 0; g < 4; ++g) {
;       const int d = 32 * dh + 8 * g + 4 * hi;
;       const u32x2 gw = *(const u32x2*)(gp + d);
;       const float v0 = ot[dh][4 * g] * siluf_(lo16(gw.x)), v1 = ot[dh][4 * g + 1] * siluf_(hi16(gw.x));
;       const float v2 = ot[dh][4 * g + 2] * siluf_(lo16(gw.y)), v3 = ot[dh][4 * g + 3] * siluf_(hi16(gw.y));
;       u32x2 w; w.x = pk2(v0, v1); w.y = pk2(v2, v3); *(u32x2*)(op + d) = w;
;     }
.LBB0_624:
	v_lshl_add_u64 v[2:3], v[172:173], 0, s[26:27]
	v_lshl_add_u64 v[6:7], v[2:3], 0, s[66:67]
	v_lshlrev_b32_e32 v0, 1, v118
	v_lshl_add_u64 v[10:11], v[6:7], 0, v[0:1]
	global_load_dwordx2 v[234:235], v[10:11], off
	global_load_dwordx2 v[236:237], v[10:11], off offset:16
	global_load_dwordx2 v[238:239], v[10:11], off offset:32
	global_load_dwordx2 v[240:241], v[10:11], off offset:48
	global_load_dwordx2 v[242:243], v[10:11], off offset:64
	global_load_dwordx2 v[244:245], v[10:11], off offset:80
	global_load_dwordx2 v[246:247], v[10:11], off offset:96
	global_load_dwordx2 v[248:249], v[10:11], off offset:112
	v_lshlrev_b32_e32 v2, 16, v220
	ds_bpermute_b32 v4, v219, v221
	v_mul_f32_e32 v2, 0xbfb8aa3b, v2
	v_exp_f32_e32 v5, v2
	ds_read2st64_b32 v[14:15], v198 offset0:160 offset1:161
	ds_read2st64_b32 v[48:49], v198 offset0:162 offset1:163
	ds_read2st64_b32 v[50:51], v198 offset0:164 offset1:165
	ds_read2st64_b32 v[52:53], v198 offset0:166 offset1:167
	v_lshlrev_b64 v[2:3], 9, v[170:171]
	s_waitcnt lgkmcnt(4)
	v_add_f32_e32 v4, v221, v4
	v_add_f32_e32 v5, 1.0, v5
	v_rcp_f32_e32 v4, v4
	v_rcp_f32_e32 v5, v5
	v_lshl_add_u64 v[2:3], s[30:31], 0, v[2:3]
	v_lshl_add_u64 v[8:9], v[2:3], 0, v[0:1]
	v_lshlrev_b32_e32 v0, 1, v120
	v_mul_f32_e32 v4, v5, v4
	v_lshl_add_u64 v[54:55], v[6:7], 0, v[0:1]
	s_waitcnt vmcnt(7)
	v_lshlrev_b32_e32 v56, 16, v234
	v_and_b32_e32 v57, 0xffff0000, v234
	v_lshlrev_b32_e32 v12, 16, v235
	v_and_b32_e32 v13, 0xffff0000, v235
	v_mul_f32_e32 v5, 0xbfb8aa3b, v56
	v_mul_f32_e32 v58, 0xbfb8aa3b, v57
	v_mul_f32_e32 v59, 0xbfb8aa3b, v12
	v_mul_f32_e32 v60, 0xbfb8aa3b, v13
	v_exp_f32_e32 v5, v5
	v_exp_f32_e32 v58, v58
	v_exp_f32_e32 v59, v59
	v_exp_f32_e32 v60, v60
	v_add_f32_e32 v5, 1.0, v5
	v_add_f32_e32 v61, 1.0, v58
	v_add_f32_e32 v62, 1.0, v59
	v_add_f32_e32 v63, 1.0, v60
	v_rcp_f32_e32 v58, v5
	v_rcp_f32_e32 v59, v61
	v_rcp_f32_e32 v60, v62
	v_rcp_f32_e32 v61, v63
	s_waitcnt lgkmcnt(3)
	v_pk_fma_f32 v[14:15], v[32:33], v[4:5], v[14:15] op_sel_hi:[1,0,1]
	s_waitcnt lgkmcnt(2)
	v_pk_fma_f32 v[32:33], v[34:35], v[4:5], v[48:49] op_sel_hi:[1,0,1]
	v_pk_mul_f32 v[34:35], v[58:59], v[56:57]
	v_pk_mul_f32 v[12:13], v[60:61], v[12:13]
	v_pk_mul_f32 v[14:15], v[14:15], v[34:35]
	v_pk_mul_f32 v[12:13], v[32:33], v[12:13]
	v_cvt_pk_bf16_f32 v14, v14, v15
	v_cvt_pk_bf16_f32 v15, v12, v13
	global_store_dwordx2 v[8:9], v[14:15], off
	v_lshl_add_u64 v[14:15], v[2:3], 0, v[0:1]
	v_lshlrev_b32_e32 v0, 1, v128
	v_lshl_add_u64 v[32:33], v[6:7], 0, v[0:1]
	s_waitcnt vmcnt(7)
	v_lshlrev_b32_e32 v34, 16, v236
	v_and_b32_e32 v35, 0xffff0000, v236
	v_lshlrev_b32_e32 v12, 16, v237
	v_and_b32_e32 v13, 0xffff0000, v237
	v_mul_f32_e32 v5, 0xbfb8aa3b, v34
	v_mul_f32_e32 v48, 0xbfb8aa3b, v35
	v_mul_f32_e32 v49, 0xbfb8aa3b, v12
	v_mul_f32_e32 v54, 0xbfb8aa3b, v13
	v_exp_f32_e32 v5, v5
	v_exp_f32_e32 v48, v48
	v_exp_f32_e32 v49, v49
	v_exp_f32_e32 v54, v54
	v_add_f32_e32 v5, 1.0, v5
	v_add_f32_e32 v55, 1.0, v48
	v_add_f32_e32 v56, 1.0, v49
	v_add_f32_e32 v57, 1.0, v54
	v_rcp_f32_e32 v48, v5
	v_rcp_f32_e32 v49, v55
	v_rcp_f32_e32 v54, v56
	v_rcp_f32_e32 v55, v57
	s_waitcnt lgkmcnt(1)
	v_pk_fma_f32 v[36:37], v[36:37], v[4:5], v[50:51] op_sel_hi:[1,0,1]
	s_waitcnt lgkmcnt(0)
	v_pk_fma_f32 v[38:39], v[38:39], v[4:5], v[52:53] op_sel_hi:[1,0,1]
	v_pk_mul_f32 v[34:35], v[48:49], v[34:35]
	v_pk_mul_f32 v[12:13], v[54:55], v[12:13]
	v_pk_mul_f32 v[34:35], v[36:37], v[34:35]
	v_pk_mul_f32 v[12:13], v[38:39], v[12:13]
	v_cvt_pk_bf16_f32 v34, v34, v35
	v_cvt_pk_bf16_f32 v35, v12, v13
	global_store_dwordx2 v[14:15], v[34:35], off
	ds_read2st64_b32 v[14:15], v198 offset0:168 offset1:169
	ds_read2st64_b32 v[32:33], v198 offset0:170 offset1:171
	ds_read2st64_b32 v[34:35], v198 offset0:172 offset1:173
	ds_read2st64_b32 v[36:37], v198 offset0:174 offset1:175
	v_lshl_add_u64 v[38:39], v[2:3], 0, v[0:1]
	v_lshlrev_b32_e32 v0, 1, v136
	v_lshl_add_u64 v[48:49], v[6:7], 0, v[0:1]
	s_waitcnt vmcnt(7)
	v_lshlrev_b32_e32 v50, 16, v238
	v_and_b32_e32 v51, 0xffff0000, v238
	v_lshlrev_b32_e32 v12, 16, v239
	v_and_b32_e32 v13, 0xffff0000, v239
	v_mul_f32_e32 v5, 0xbfb8aa3b, v50
	v_mul_f32_e32 v52, 0xbfb8aa3b, v51
	v_mul_f32_e32 v53, 0xbfb8aa3b, v12
	v_mul_f32_e32 v54, 0xbfb8aa3b, v13
	v_exp_f32_e32 v5, v5
	v_exp_f32_e32 v52, v52
	v_exp_f32_e32 v53, v53
	v_exp_f32_e32 v54, v54
	v_add_f32_e32 v5, 1.0, v5
	v_add_f32_e32 v55, 1.0, v52
	v_add_f32_e32 v56, 1.0, v53
	v_add_f32_e32 v57, 1.0, v54
	v_rcp_f32_e32 v52, v5
	v_rcp_f32_e32 v53, v55
	v_rcp_f32_e32 v54, v56
	v_rcp_f32_e32 v55, v57
	s_waitcnt lgkmcnt(3)
	v_pk_fma_f32 v[14:15], v[40:41], v[4:5], v[14:15] op_sel_hi:[1,0,1]
	s_waitcnt lgkmcnt(2)
	v_pk_fma_f32 v[32:33], v[42:43], v[4:5], v[32:33] op_sel_hi:[1,0,1]
	v_pk_mul_f32 v[40:41], v[52:53], v[50:51]
	v_pk_mul_f32 v[12:13], v[54:55], v[12:13]
	v_pk_mul_f32 v[14:15], v[14:15], v[40:41]
	v_pk_mul_f32 v[12:13], v[32:33], v[12:13]
	v_cvt_pk_bf16_f32 v14, v14, v15
	v_cvt_pk_bf16_f32 v15, v12, v13
	global_store_dwordx2 v[38:39], v[14:15], off
	v_lshl_add_u64 v[14:15], v[2:3], 0, v[0:1]
	s_waitcnt vmcnt(7)
	v_lshlrev_b32_e32 v32, 16, v240
	v_and_b32_e32 v33, 0xffff0000, v240
	v_lshlrev_b32_e32 v12, 16, v241
	v_and_b32_e32 v13, 0xffff0000, v241
	v_mul_f32_e32 v0, 0xbfb8aa3b, v32
	v_mul_f32_e32 v5, 0xbfb8aa3b, v33
	v_mul_f32_e32 v38, 0xbfb8aa3b, v12
	v_mul_f32_e32 v39, 0xbfb8aa3b, v13
	v_exp_f32_e32 v0, v0
	v_exp_f32_e32 v5, v5
	v_exp_f32_e32 v38, v38
	v_exp_f32_e32 v39, v39
	v_add_f32_e32 v0, 1.0, v0
	v_add_f32_e32 v5, 1.0, v5
	v_add_f32_e32 v40, 1.0, v38
	v_add_f32_e32 v41, 1.0, v39
	v_rcp_f32_e32 v38, v0
	v_rcp_f32_e32 v39, v5
	v_rcp_f32_e32 v40, v40
	v_rcp_f32_e32 v41, v41
	s_waitcnt lgkmcnt(1)
; __device__ __forceinline__ unsigned pk2(float lo, float hi) { f32x2_t v = {lo, hi}; bf16x2_t b = __builtin_convertvector(v, bf16x2_t); return __builtin_bit_cast(unsigned, b); }
; __device__ __forceinline__ float lo16(unsigned w) { return __uint_as_float(w << 16); }
; __device__ __forceinline__ float hi16(unsigned w) { return __uint_as_float(w & 0xffff0000u); }
; __device__ __forceinline__ float frcp(float x) { return __builtin_amdgcn_rcpf(x); }
; __device__ __forceinline__ float siluf_(float x) { return x * sigmoidf_(x); }
; __device__ __forceinline__ float merge_l(float l) { return l + __shfl_xor(l, 32); }
; __device__ __forceinline__ void nsa_unit(int b, int qt, const bf16_t* proj, const bf16_t* vt, const bf16_t* kc, const bf16_t* vcT, bf16_t* ab0, LAS unsigned char* lds, int tid, int wid, int lane) {
;     ...
;     const float sc = g2 * frcp(merge_l(st.l));
; #pragma unroll
;     for (int r = 0; r < 16; ++r) { ot[0][r] = stash[r * 64] + sc * st.o[0][r]; ot[1][r] = stash[(16 + r) * 64] + sc * st.o[1][r]; }
;   }
;   const bf16_t* gp = proj + tok * NP + C_GATE + head * 64;
;   bf16_t* op = ab0 + tok * 256 + head * 64;
; #pragma unroll
;   for (int dh = 0; dh < 2; ++dh)
; #pragma unroll
;     for (int g = 0; g < 4; ++g) {
;       const int d = 32 * dh + 8 * g + 4 * hi;
;       const u32x2 gw = *(const u32x2*)(gp + d);
;       const float v0 = ot[dh][4 * g] * siluf_(lo16(gw.x)), v1 = ot[dh][4 * g + 1] * siluf_(hi16(gw.x));
;       const float v2 = ot[dh][4 * g + 2] * siluf_(lo16(gw.y)), v3 = ot[dh][4 * g + 3] * siluf_(hi16(gw.y));
;       u32x2 w; w.x = pk2(v0, v1); w.y = pk2(v2, v3); *(u32x2*)(op + d) = w;
;     }
	v_pk_fma_f32 v[34:35], v[44:45], v[4:5], v[34:35] op_sel_hi:[1,0,1]
	s_waitcnt lgkmcnt(0)
	v_pk_fma_f32 v[36:37], v[46:47], v[4:5], v[36:37] op_sel_hi:[1,0,1]
	v_pk_mul_f32 v[32:33], v[38:39], v[32:33]
	v_pk_mul_f32 v[12:13], v[40:41], v[12:13]
	v_pk_mul_f32 v[32:33], v[34:35], v[32:33]
	v_pk_mul_f32 v[12:13], v[36:37], v[12:13]
	v_cvt_pk_bf16_f32 v32, v32, v33
	v_cvt_pk_bf16_f32 v33, v12, v13
	global_store_dwordx2 v[14:15], v[32:33], off
	ds_read2st64_b32 v[12:13], v198 offset0:176 offset1:177
	ds_read2st64_b32 v[14:15], v198 offset0:178 offset1:179
	ds_read2st64_b32 v[32:33], v198 offset0:180 offset1:181
	ds_read2st64_b32 v[34:35], v198 offset0:182 offset1:183
	v_lshlrev_b32_e32 v0, 1, v122
	v_lshl_add_u64 v[36:37], v[6:7], 0, v[0:1]
	s_waitcnt vmcnt(7)
	v_lshlrev_b32_e32 v38, 16, v242
	v_and_b32_e32 v39, 0xffff0000, v242
	v_lshlrev_b32_e32 v10, 16, v243
	v_and_b32_e32 v11, 0xffff0000, v243
	v_mul_f32_e32 v5, 0xbfb8aa3b, v38
	v_mul_f32_e32 v40, 0xbfb8aa3b, v39
	v_mul_f32_e32 v41, 0xbfb8aa3b, v10
	v_mul_f32_e32 v42, 0xbfb8aa3b, v11
	v_exp_f32_e32 v5, v5
	v_exp_f32_e32 v40, v40
	v_exp_f32_e32 v41, v41
	v_exp_f32_e32 v42, v42
	v_add_f32_e32 v5, 1.0, v5
	v_add_f32_e32 v43, 1.0, v40
	v_add_f32_e32 v44, 1.0, v41
	v_add_f32_e32 v45, 1.0, v42
	v_rcp_f32_e32 v40, v5
	v_rcp_f32_e32 v41, v43
	v_rcp_f32_e32 v42, v44
	v_rcp_f32_e32 v43, v45
	s_waitcnt lgkmcnt(3)
	v_pk_fma_f32 v[12:13], v[16:17], v[4:5], v[12:13] op_sel_hi:[1,0,1]
	s_waitcnt lgkmcnt(2)
	v_pk_fma_f32 v[14:15], v[18:19], v[4:5], v[14:15] op_sel_hi:[1,0,1]
	v_pk_mul_f32 v[16:17], v[40:41], v[38:39]
	v_pk_mul_f32 v[10:11], v[42:43], v[10:11]
	v_pk_mul_f32 v[12:13], v[12:13], v[16:17]
	v_pk_mul_f32 v[10:11], v[14:15], v[10:11]
	v_cvt_pk_bf16_f32 v12, v12, v13
	v_cvt_pk_bf16_f32 v13, v10, v11
	global_store_dwordx2 v[8:9], v[12:13], off offset:64
	v_lshl_add_u64 v[10:11], v[2:3], 0, v[0:1]
	v_lshlrev_b32_e32 v0, 1, v130
	v_lshl_add_u64 v[12:13], v[6:7], 0, v[0:1]
	s_waitcnt vmcnt(7)
	v_lshlrev_b32_e32 v14, 16, v244
	v_and_b32_e32 v15, 0xffff0000, v244
	v_lshlrev_b32_e32 v8, 16, v245
	v_and_b32_e32 v9, 0xffff0000, v245
	v_mul_f32_e32 v5, 0xbfb8aa3b, v14
	v_mul_f32_e32 v16, 0xbfb8aa3b, v15
	v_mul_f32_e32 v17, 0xbfb8aa3b, v8
	v_mul_f32_e32 v18, 0xbfb8aa3b, v9
	v_exp_f32_e32 v5, v5
	v_exp_f32_e32 v16, v16
	v_exp_f32_e32 v17, v17
	v_exp_f32_e32 v18, v18
	v_add_f32_e32 v5, 1.0, v5
	v_add_f32_e32 v19, 1.0, v16
	v_add_f32_e32 v36, 1.0, v17
	v_add_f32_e32 v37, 1.0, v18
	v_rcp_f32_e32 v16, v5
	v_rcp_f32_e32 v17, v19
	v_rcp_f32_e32 v18, v36
	v_rcp_f32_e32 v19, v37
	s_waitcnt lgkmcnt(1)
	v_pk_fma_f32 v[20:21], v[20:21], v[4:5], v[32:33] op_sel_hi:[1,0,1]
	s_waitcnt lgkmcnt(0)
	v_pk_fma_f32 v[22:23], v[22:23], v[4:5], v[34:35] op_sel_hi:[1,0,1]
	v_pk_mul_f32 v[14:15], v[16:17], v[14:15]
	v_pk_mul_f32 v[8:9], v[18:19], v[8:9]
	v_pk_mul_f32 v[14:15], v[20:21], v[14:15]
	v_pk_mul_f32 v[8:9], v[22:23], v[8:9]
	v_cvt_pk_bf16_f32 v14, v14, v15
	v_cvt_pk_bf16_f32 v15, v8, v9
	global_store_dwordx2 v[10:11], v[14:15], off
	ds_read2st64_b32 v[10:11], v198 offset0:184 offset1:185
	ds_read2st64_b32 v[12:13], v198 offset0:186 offset1:187
	ds_read2st64_b32 v[14:15], v198 offset0:188 offset1:189
	ds_read2st64_b32 v[16:17], v198 offset0:190 offset1:191
	v_lshl_add_u64 v[18:19], v[2:3], 0, v[0:1]
	v_lshlrev_b32_e32 v0, 1, v138
	v_lshl_add_u64 v[6:7], v[6:7], 0, v[0:1]
	v_lshl_add_u64 v[2:3], v[2:3], 0, v[0:1]
	s_waitcnt vmcnt(7)
	v_lshlrev_b32_e32 v20, 16, v246
	v_and_b32_e32 v21, 0xffff0000, v246
	v_lshlrev_b32_e32 v8, 16, v247
	v_and_b32_e32 v9, 0xffff0000, v247
	v_mul_f32_e32 v5, 0xbfb8aa3b, v20
	v_mul_f32_e32 v22, 0xbfb8aa3b, v21
	v_mul_f32_e32 v23, 0xbfb8aa3b, v8
	v_mul_f32_e32 v32, 0xbfb8aa3b, v9
	v_exp_f32_e32 v5, v5
	v_exp_f32_e32 v22, v22
	v_exp_f32_e32 v23, v23
	v_exp_f32_e32 v32, v32
	v_add_f32_e32 v5, 1.0, v5
	v_add_f32_e32 v33, 1.0, v22
	v_add_f32_e32 v34, 1.0, v23
	v_add_f32_e32 v35, 1.0, v32
	v_rcp_f32_e32 v22, v5
	v_rcp_f32_e32 v23, v33
	v_rcp_f32_e32 v32, v34
	v_rcp_f32_e32 v33, v35
	s_waitcnt lgkmcnt(3)
	v_pk_fma_f32 v[10:11], v[24:25], v[4:5], v[10:11] op_sel_hi:[1,0,1]
	s_waitcnt lgkmcnt(2)
	v_pk_fma_f32 v[12:13], v[26:27], v[4:5], v[12:13] op_sel_hi:[1,0,1]
	v_pk_mul_f32 v[20:21], v[22:23], v[20:21]
	v_pk_mul_f32 v[8:9], v[32:33], v[8:9]
	v_pk_mul_f32 v[10:11], v[10:11], v[20:21]
	v_pk_mul_f32 v[8:9], v[12:13], v[8:9]
	v_cvt_pk_bf16_f32 v10, v10, v11
	v_cvt_pk_bf16_f32 v11, v8, v9
	global_store_dwordx2 v[18:19], v[10:11], off
	s_waitcnt vmcnt(7)
	v_lshlrev_b32_e32 v8, 16, v248
	v_and_b32_e32 v9, 0xffff0000, v248
	v_lshlrev_b32_e32 v6, 16, v249
	v_and_b32_e32 v7, 0xffff0000, v249
	v_mul_f32_e32 v0, 0xbfb8aa3b, v8
	v_mul_f32_e32 v5, 0xbfb8aa3b, v9
	v_mul_f32_e32 v10, 0xbfb8aa3b, v6
	v_mul_f32_e32 v11, 0xbfb8aa3b, v7
	v_exp_f32_e32 v0, v0
	v_exp_f32_e32 v5, v5
	v_exp_f32_e32 v10, v10
	v_exp_f32_e32 v11, v11
	v_add_f32_e32 v0, 1.0, v0
	v_add_f32_e32 v5, 1.0, v5
	v_add_f32_e32 v12, 1.0, v10
	v_add_f32_e32 v13, 1.0, v11
	v_rcp_f32_e32 v10, v0
	v_rcp_f32_e32 v11, v5
	v_rcp_f32_e32 v12, v12
	v_rcp_f32_e32 v13, v13
	s_waitcnt lgkmcnt(1)
	v_pk_fma_f32 v[14:15], v[28:29], v[4:5], v[14:15] op_sel_hi:[1,0,1]
	s_waitcnt lgkmcnt(0)
	v_pk_fma_f32 v[4:5], v[30:31], v[4:5], v[16:17] op_sel_hi:[1,0,1]
	v_pk_mul_f32 v[8:9], v[10:11], v[8:9]
	v_pk_mul_f32 v[6:7], v[12:13], v[6:7]
	v_pk_mul_f32 v[8:9], v[14:15], v[8:9]
	v_pk_mul_f32 v[4:5], v[4:5], v[6:7]
	v_cvt_pk_bf16_f32 v6, v8, v9
	v_cvt_pk_bf16_f32 v7, v4, v5
	global_store_dwordx2 v[2:3], v[6:7], off
	s_barrier

; __device__ __forceinline__ unsigned pk2(float lo, float hi) { f32x2_t v = {lo, hi}; bf16x2_t b = __builtin_convertvector(v, bf16x2_t); return __builtin_bit_cast(unsigned, b); }
; __device__ __forceinline__ float lo16(unsigned w) { return __uint_as_float(w << 16); }
; __device__ __forceinline__ float hi16(unsigned w) { return __uint_as_float(w & 0xffff0000u); }
; __device__ __forceinline__ float frcp(float x) { return __builtin_amdgcn_rcpf(x); }
; __device__ __forceinline__ float siluf_(float x) { return x * sigmoidf_(x); }
; __device__ __forceinline__ float merge_l(float l) { return l + __shfl_xor(l, 32); }
; __device__ __forceinline__ void fox_unit(int b, int h, int qt, const bf16_t* proj, const bf16_t* vt, const float* c2, const float* kn, bf16_t* ab3, LAS unsigned char* lds, int tid, int wid, int lane) {
;     ...
;   const float inv = frcp(merge_l(st.l));
;   const bf16_t* gp = proj + tok * NP + C_GATE + 768 + h * 64;
;   bf16_t* op = ab3 + tok * 256 + h * 64;
; #pragma unroll
;   for (int dh = 0; dh < 2; ++dh)
; #pragma unroll
;     for (int g = 0; g < 4; ++g) {
;       const int d = 32 * dh + 8 * g + 4 * hi;
;       const u32x2 gw = *(const u32x2*)(gp + d);
;       const float v0 = st.o[dh][4 * g] * inv * siluf_(lo16(gw.x)), v1 = st.o[dh][4 * g + 1] * inv * siluf_(hi16(gw.x));
;       const float v2 = st.o[dh][4 * g + 2] * inv * siluf_(lo16(gw.y)), v3 = st.o[dh][4 * g + 3] * inv * siluf_(hi16(gw.y));
;       u32x2 w; w.x = pk2(v0, v1); w.y = pk2(v2, v3); *(u32x2*)(op + d) = w;
;     }
.LBB0_661:
	s_mov_b32 s1, s27
	v_lshl_add_u64 v[2:3], v[172:173], 0, s[0:1]
	s_mov_b64 s[14:15], 0x1900
	v_lshl_add_u64 v[6:7], v[2:3], 0, s[14:15]
	v_lshlrev_b32_e32 v0, 1, v118
	v_lshl_add_u64 v[10:11], v[6:7], 0, v[0:1]
	global_load_dwordx2 v[234:235], v[10:11], off
	global_load_dwordx2 v[236:237], v[10:11], off offset:16
	global_load_dwordx2 v[238:239], v[10:11], off offset:32
	global_load_dwordx2 v[240:241], v[10:11], off offset:48
	global_load_dwordx2 v[242:243], v[10:11], off offset:64
	global_load_dwordx2 v[244:245], v[10:11], off offset:80
	global_load_dwordx2 v[246:247], v[10:11], off offset:96
	global_load_dwordx2 v[248:249], v[10:11], off offset:112
	ds_bpermute_b32 v4, v175, v220
	v_lshlrev_b64 v[2:3], 9, v[170:171]
	v_lshl_add_u64 v[2:3], s[28:29], 0, v[2:3]
	v_lshl_add_u64 v[2:3], v[2:3], 0, s[0:1]
	v_lshl_add_u64 v[8:9], v[2:3], 0, v[0:1]
	s_waitcnt lgkmcnt(0)
	v_add_f32_e32 v4, v220, v4
	v_rcp_f32_e32 v4, v4
	v_lshlrev_b32_e32 v0, 1, v120
	v_lshl_add_u64 v[14:15], v[6:7], 0, v[0:1]
	s_mov_b64 s[0:1], 0
	s_waitcnt vmcnt(7)
	v_lshlrev_b32_e32 v48, 16, v234
	v_and_b32_e32 v49, 0xffff0000, v234
	v_lshlrev_b32_e32 v12, 16, v235
	v_and_b32_e32 v13, 0xffff0000, v235
	v_mul_f32_e32 v5, 0xbfb8aa3b, v48
	v_mul_f32_e32 v50, 0xbfb8aa3b, v49
	v_mul_f32_e32 v51, 0xbfb8aa3b, v12
	v_mul_f32_e32 v52, 0xbfb8aa3b, v13
	v_exp_f32_e32 v5, v5
	v_exp_f32_e32 v50, v50
	v_exp_f32_e32 v51, v51
	v_exp_f32_e32 v52, v52
	v_add_f32_e32 v5, 1.0, v5
	v_add_f32_e32 v53, 1.0, v50
	v_add_f32_e32 v54, 1.0, v51
	v_add_f32_e32 v55, 1.0, v52
	v_rcp_f32_e32 v50, v5
	v_rcp_f32_e32 v51, v53
	v_rcp_f32_e32 v52, v54
	v_rcp_f32_e32 v53, v55
	v_pk_mul_f32 v[32:33], v[32:33], v[4:5] op_sel_hi:[1,0]
	v_pk_mul_f32 v[34:35], v[34:35], v[4:5] op_sel_hi:[1,0]
	v_pk_mul_f32 v[48:49], v[50:51], v[48:49]
	v_pk_mul_f32 v[12:13], v[52:53], v[12:13]
	v_pk_mul_f32 v[32:33], v[32:33], v[48:49]
	v_pk_mul_f32 v[12:13], v[34:35], v[12:13]
	v_cvt_pk_bf16_f32 v32, v32, v33
	v_cvt_pk_bf16_f32 v33, v12, v13
	global_store_dwordx2 v[8:9], v[32:33], off
	v_lshl_add_u64 v[14:15], v[2:3], 0, v[0:1]
	v_lshlrev_b32_e32 v0, 1, v128
	v_lshl_add_u64 v[32:33], v[6:7], 0, v[0:1]
	s_waitcnt vmcnt(7)
	v_lshlrev_b32_e32 v34, 16, v236
	v_and_b32_e32 v35, 0xffff0000, v236
	v_lshlrev_b32_e32 v12, 16, v237
	v_and_b32_e32 v13, 0xffff0000, v237
	v_mul_f32_e32 v5, 0xbfb8aa3b, v34
	v_mul_f32_e32 v48, 0xbfb8aa3b, v35
	v_mul_f32_e32 v49, 0xbfb8aa3b, v12
	v_mul_f32_e32 v50, 0xbfb8aa3b, v13
	v_exp_f32_e32 v5, v5
	v_exp_f32_e32 v48, v48
	v_exp_f32_e32 v49, v49
	v_exp_f32_e32 v50, v50
	v_add_f32_e32 v5, 1.0, v5
	v_add_f32_e32 v51, 1.0, v48
	v_add_f32_e32 v52, 1.0, v49
	v_add_f32_e32 v53, 1.0, v50
	v_rcp_f32_e32 v48, v5
	v_rcp_f32_e32 v49, v51
	v_rcp_f32_e32 v50, v52
	v_rcp_f32_e32 v51, v53
	v_pk_mul_f32 v[36:37], v[36:37], v[4:5] op_sel_hi:[1,0]
	v_pk_mul_f32 v[38:39], v[38:39], v[4:5] op_sel_hi:[1,0]
	v_pk_mul_f32 v[34:35], v[48:49], v[34:35]
	v_pk_mul_f32 v[12:13], v[50:51], v[12:13]
	v_pk_mul_f32 v[34:35], v[36:37], v[34:35]
	v_pk_mul_f32 v[12:13], v[38:39], v[12:13]
	v_cvt_pk_bf16_f32 v34, v34, v35
	v_cvt_pk_bf16_f32 v35, v12, v13
	global_store_dwordx2 v[14:15], v[34:35], off
	v_lshl_add_u64 v[14:15], v[2:3], 0, v[0:1]
	v_lshlrev_b32_e32 v0, 1, v136
	v_lshl_add_u64 v[32:33], v[6:7], 0, v[0:1]
	s_waitcnt vmcnt(7)
	v_lshlrev_b32_e32 v34, 16, v238
	v_and_b32_e32 v35, 0xffff0000, v238
	v_lshlrev_b32_e32 v12, 16, v239
	v_and_b32_e32 v13, 0xffff0000, v239
	v_mul_f32_e32 v5, 0xbfb8aa3b, v34
	v_mul_f32_e32 v36, 0xbfb8aa3b, v35
	v_mul_f32_e32 v37, 0xbfb8aa3b, v12
	v_mul_f32_e32 v38, 0xbfb8aa3b, v13
	v_exp_f32_e32 v5, v5
	v_exp_f32_e32 v36, v36
	v_exp_f32_e32 v37, v37
	v_exp_f32_e32 v38, v38
	v_add_f32_e32 v5, 1.0, v5
	v_add_f32_e32 v39, 1.0, v36
	v_add_f32_e32 v48, 1.0, v37
	v_add_f32_e32 v49, 1.0, v38
	v_rcp_f32_e32 v36, v5
	v_rcp_f32_e32 v37, v39
	v_rcp_f32_e32 v38, v48
	v_rcp_f32_e32 v39, v49
	v_pk_mul_f32 v[40:41], v[40:41], v[4:5] op_sel_hi:[1,0]
	v_pk_mul_f32 v[42:43], v[42:43], v[4:5] op_sel_hi:[1,0]
	v_pk_mul_f32 v[34:35], v[36:37], v[34:35]
	v_pk_mul_f32 v[12:13], v[38:39], v[12:13]
	v_pk_mul_f32 v[34:35], v[40:41], v[34:35]
	v_pk_mul_f32 v[12:13], v[42:43], v[12:13]
	v_cvt_pk_bf16_f32 v34, v34, v35
	v_cvt_pk_bf16_f32 v35, v12, v13
	global_store_dwordx2 v[14:15], v[34:35], off
	v_lshl_add_u64 v[14:15], v[2:3], 0, v[0:1]
	s_waitcnt vmcnt(7)
; __device__ __forceinline__ unsigned pk2(float lo, float hi) { f32x2_t v = {lo, hi}; bf16x2_t b = __builtin_convertvector(v, bf16x2_t); return __builtin_bit_cast(unsigned, b); }
; __device__ __forceinline__ float lo16(unsigned w) { return __uint_as_float(w << 16); }
; __device__ __forceinline__ float hi16(unsigned w) { return __uint_as_float(w & 0xffff0000u); }
; __device__ __forceinline__ float frcp(float x) { return __builtin_amdgcn_rcpf(x); }
; __device__ __forceinline__ float siluf_(float x) { return x * sigmoidf_(x); }
; __device__ __forceinline__ float merge_l(float l) { return l + __shfl_xor(l, 32); }
; __device__ __forceinline__ void fox_unit(int b, int h, int qt, const bf16_t* proj, const bf16_t* vt, const float* c2, const float* kn, bf16_t* ab3, LAS unsigned char* lds, int tid, int wid, int lane) {
;     ...
;   const float inv = frcp(merge_l(st.l));
;   const bf16_t* gp = proj + tok * NP + C_GATE + 768 + h * 64;
;   bf16_t* op = ab3 + tok * 256 + h * 64;
; #pragma unroll
;   for (int dh = 0; dh < 2; ++dh)
; #pragma unroll
;     for (int g = 0; g < 4; ++g) {
;       const int d = 32 * dh + 8 * g + 4 * hi;
;       const u32x2 gw = *(const u32x2*)(gp + d);
;       const float v0 = st.o[dh][4 * g] * inv * siluf_(lo16(gw.x)), v1 = st.o[dh][4 * g + 1] * inv * siluf_(hi16(gw.x));
;       const float v2 = st.o[dh][4 * g + 2] * inv * siluf_(lo16(gw.y)), v3 = st.o[dh][4 * g + 3] * inv * siluf_(hi16(gw.y));
;       u32x2 w; w.x = pk2(v0, v1); w.y = pk2(v2, v3); *(u32x2*)(op + d) = w;
;     }
	v_lshlrev_b32_e32 v32, 16, v240
	v_and_b32_e32 v33, 0xffff0000, v240
	v_lshlrev_b32_e32 v12, 16, v241
	v_and_b32_e32 v13, 0xffff0000, v241
	v_mul_f32_e32 v0, 0xbfb8aa3b, v32
	v_mul_f32_e32 v5, 0xbfb8aa3b, v33
	v_mul_f32_e32 v34, 0xbfb8aa3b, v12
	v_mul_f32_e32 v35, 0xbfb8aa3b, v13
	v_exp_f32_e32 v0, v0
	v_exp_f32_e32 v5, v5
	v_exp_f32_e32 v34, v34
	v_exp_f32_e32 v35, v35
	v_add_f32_e32 v0, 1.0, v0
	v_add_f32_e32 v5, 1.0, v5
	v_add_f32_e32 v36, 1.0, v34
	v_add_f32_e32 v37, 1.0, v35
	v_rcp_f32_e32 v34, v0
	v_rcp_f32_e32 v35, v5
	v_rcp_f32_e32 v36, v36
	v_rcp_f32_e32 v37, v37
	v_pk_mul_f32 v[38:39], v[44:45], v[4:5] op_sel_hi:[1,0]
	v_pk_mul_f32 v[40:41], v[46:47], v[4:5] op_sel_hi:[1,0]
	v_pk_mul_f32 v[32:33], v[34:35], v[32:33]
	v_pk_mul_f32 v[12:13], v[36:37], v[12:13]
	v_pk_mul_f32 v[32:33], v[38:39], v[32:33]
	v_pk_mul_f32 v[12:13], v[40:41], v[12:13]
	v_cvt_pk_bf16_f32 v32, v32, v33
	v_cvt_pk_bf16_f32 v33, v12, v13
	global_store_dwordx2 v[14:15], v[32:33], off
	v_lshlrev_b32_e32 v0, 1, v122
	v_lshl_add_u64 v[12:13], v[6:7], 0, v[0:1]
	s_waitcnt vmcnt(7)
	v_lshlrev_b32_e32 v14, 16, v242
	v_and_b32_e32 v15, 0xffff0000, v242
	v_lshlrev_b32_e32 v10, 16, v243
	v_and_b32_e32 v11, 0xffff0000, v243
	v_mul_f32_e32 v5, 0xbfb8aa3b, v14
	v_mul_f32_e32 v32, 0xbfb8aa3b, v15
	v_mul_f32_e32 v33, 0xbfb8aa3b, v10
	v_mul_f32_e32 v34, 0xbfb8aa3b, v11
	v_exp_f32_e32 v5, v5
	v_exp_f32_e32 v32, v32
	v_exp_f32_e32 v33, v33
	v_exp_f32_e32 v34, v34
	v_add_f32_e32 v5, 1.0, v5
	v_add_f32_e32 v35, 1.0, v32
	v_add_f32_e32 v36, 1.0, v33
	v_add_f32_e32 v37, 1.0, v34
	v_rcp_f32_e32 v32, v5
	v_rcp_f32_e32 v33, v35
	v_rcp_f32_e32 v34, v36
	v_rcp_f32_e32 v35, v37
	v_pk_mul_f32 v[16:17], v[16:17], v[4:5] op_sel_hi:[1,0]
	v_pk_mul_f32 v[18:19], v[18:19], v[4:5] op_sel_hi:[1,0]
	v_pk_mul_f32 v[14:15], v[32:33], v[14:15]
	v_pk_mul_f32 v[10:11], v[34:35], v[10:11]
	v_pk_mul_f32 v[14:15], v[16:17], v[14:15]
	v_pk_mul_f32 v[10:11], v[18:19], v[10:11]
	v_cvt_pk_bf16_f32 v14, v14, v15
	v_cvt_pk_bf16_f32 v15, v10, v11
	global_store_dwordx2 v[8:9], v[14:15], off offset:64
	v_lshl_add_u64 v[10:11], v[2:3], 0, v[0:1]
	v_lshlrev_b32_e32 v0, 1, v130
	v_lshl_add_u64 v[12:13], v[6:7], 0, v[0:1]
	s_waitcnt vmcnt(7)
	v_lshlrev_b32_e32 v14, 16, v244
	v_and_b32_e32 v15, 0xffff0000, v244
	v_lshlrev_b32_e32 v8, 16, v245
	v_and_b32_e32 v9, 0xffff0000, v245
	v_mul_f32_e32 v5, 0xbfb8aa3b, v14
	v_mul_f32_e32 v16, 0xbfb8aa3b, v15
	v_mul_f32_e32 v17, 0xbfb8aa3b, v8
	v_mul_f32_e32 v18, 0xbfb8aa3b, v9
	v_exp_f32_e32 v5, v5
	v_exp_f32_e32 v16, v16
	v_exp_f32_e32 v17, v17
	v_exp_f32_e32 v18, v18
	v_add_f32_e32 v5, 1.0, v5
	v_add_f32_e32 v19, 1.0, v16
	v_add_f32_e32 v32, 1.0, v17
	v_add_f32_e32 v33, 1.0, v18
	v_rcp_f32_e32 v16, v5
	v_rcp_f32_e32 v17, v19
	v_rcp_f32_e32 v18, v32
	v_rcp_f32_e32 v19, v33
	v_pk_mul_f32 v[20:21], v[20:21], v[4:5] op_sel_hi:[1,0]
	v_pk_mul_f32 v[22:23], v[22:23], v[4:5] op_sel_hi:[1,0]
	v_pk_mul_f32 v[14:15], v[16:17], v[14:15]
	v_pk_mul_f32 v[8:9], v[18:19], v[8:9]
	v_pk_mul_f32 v[14:15], v[20:21], v[14:15]
	v_pk_mul_f32 v[8:9], v[22:23], v[8:9]
	v_cvt_pk_bf16_f32 v14, v14, v15
	v_cvt_pk_bf16_f32 v15, v8, v9
	global_store_dwordx2 v[10:11], v[14:15], off
	v_lshl_add_u64 v[10:11], v[2:3], 0, v[0:1]
	v_lshlrev_b32_e32 v0, 1, v138
	v_lshl_add_u64 v[6:7], v[6:7], 0, v[0:1]
	v_lshl_add_u64 v[2:3], v[2:3], 0, v[0:1]
	s_waitcnt vmcnt(7)
	v_lshlrev_b32_e32 v12, 16, v246
	v_and_b32_e32 v13, 0xffff0000, v246
	v_lshlrev_b32_e32 v8, 16, v247
	v_and_b32_e32 v9, 0xffff0000, v247
	v_mul_f32_e32 v5, 0xbfb8aa3b, v12
	v_mul_f32_e32 v14, 0xbfb8aa3b, v13
	v_mul_f32_e32 v15, 0xbfb8aa3b, v8
	v_mul_f32_e32 v16, 0xbfb8aa3b, v9
	v_exp_f32_e32 v5, v5
	v_exp_f32_e32 v14, v14
	v_exp_f32_e32 v15, v15
	v_exp_f32_e32 v16, v16
	v_add_f32_e32 v5, 1.0, v5
	v_add_f32_e32 v17, 1.0, v14
	v_add_f32_e32 v18, 1.0, v15
	v_add_f32_e32 v19, 1.0, v16
	v_rcp_f32_e32 v14, v5
	v_rcp_f32_e32 v15, v17
	v_rcp_f32_e32 v16, v18
	v_rcp_f32_e32 v17, v19
	v_pk_mul_f32 v[18:19], v[24:25], v[4:5] op_sel_hi:[1,0]
	v_pk_mul_f32 v[20:21], v[26:27], v[4:5] op_sel_hi:[1,0]
	v_pk_mul_f32 v[12:13], v[14:15], v[12:13]
	v_pk_mul_f32 v[8:9], v[16:17], v[8:9]
	v_pk_mul_f32 v[12:13], v[18:19], v[12:13]
	v_pk_mul_f32 v[8:9], v[20:21], v[8:9]
	v_cvt_pk_bf16_f32 v12, v12, v13
	v_cvt_pk_bf16_f32 v13, v8, v9
	global_store_dwordx2 v[10:11], v[12:13], off
	s_waitcnt vmcnt(7)
	v_lshlrev_b32_e32 v8, 16, v248
	v_and_b32_e32 v9, 0xffff0000, v248
	v_lshlrev_b32_e32 v6, 16, v249
	v_and_b32_e32 v7, 0xffff0000, v249
	v_mul_f32_e32 v0, 0xbfb8aa3b, v8
	v_mul_f32_e32 v5, 0xbfb8aa3b, v9
	v_mul_f32_e32 v10, 0xbfb8aa3b, v6
	v_mul_f32_e32 v11, 0xbfb8aa3b, v7
	v_exp_f32_e32 v0, v0
	v_exp_f32_e32 v5, v5
	v_exp_f32_e32 v10, v10
	v_exp_f32_e32 v11, v11
	v_add_f32_e32 v0, 1.0, v0
	v_add_f32_e32 v5, 1.0, v5
	v_add_f32_e32 v12, 1.0, v10
	v_add_f32_e32 v13, 1.0, v11
	v_rcp_f32_e32 v10, v0
	v_rcp_f32_e32 v11, v5
	v_rcp_f32_e32 v12, v12
	v_rcp_f32_e32 v13, v13
	v_pk_mul_f32 v[14:15], v[28:29], v[4:5] op_sel_hi:[1,0]
	v_pk_mul_f32 v[4:5], v[30:31], v[4:5] op_sel_hi:[1,0]
	v_pk_mul_f32 v[8:9], v[10:11], v[8:9]
	v_pk_mul_f32 v[6:7], v[12:13], v[6:7]
	v_pk_mul_f32 v[8:9], v[14:15], v[8:9]
	v_pk_mul_f32 v[4:5], v[4:5], v[6:7]
	v_cvt_pk_bf16_f32 v6, v8, v9
	v_cvt_pk_bf16_f32 v7, v4, v5
	global_store_dwordx2 v[2:3], v[6:7], off

; __device__ __forceinline__ unsigned pk2(float lo, float hi) { f32x2_t v = {lo, hi}; bf16x2_t b = __builtin_convertvector(v, bf16x2_t); return __builtin_bit_cast(unsigned, b); }
; __device__ __forceinline__ float lo16(unsigned w) { return __uint_as_float(w << 16); }
; __device__ __forceinline__ float hi16(unsigned w) { return __uint_as_float(w & 0xffff0000u); }
; __device__ __forceinline__ float frcp(float x) { return __builtin_amdgcn_rcpf(x); }
; __device__ __forceinline__ float siluf_(float x) { return x * sigmoidf_(x); }
; __device__ __forceinline__ float merge_l(float l) { return l + __shfl_xor(l, 32); }
; __device__ __forceinline__ void nsa_unit(int b, int qt, const bf16_t* proj, const bf16_t* vt, const bf16_t* kc, const bf16_t* vcT, bf16_t* ab0, LAS unsigned char* lds, int tid, int wid, int lane) {
;     ...
;     const float sc = g2 * frcp(merge_l(st.l));
; #pragma unroll
;     for (int r = 0; r < 16; ++r) { ot[0][r] = stash[r * 64] + sc * st.o[0][r]; ot[1][r] = stash[(16 + r) * 64] + sc * st.o[1][r]; }
;   }
;   const bf16_t* gp = proj + tok * NP + C_GATE + head * 64;
;   bf16_t* op = ab0 + tok * 256 + head * 64;
; #pragma unroll
;   for (int dh = 0; dh < 2; ++dh)
; #pragma unroll
;     for (int g = 0; g < 4; ++g) {
;       const int d = 32 * dh + 8 * g + 4 * hi;
;       const u32x2 gw = *(const u32x2*)(gp + d);
;       const float v0 = ot[dh][4 * g] * siluf_(lo16(gw.x)), v1 = ot[dh][4 * g + 1] * siluf_(hi16(gw.x));
;       const float v2 = ot[dh][4 * g + 2] * siluf_(lo16(gw.y)), v3 = ot[dh][4 * g + 3] * siluf_(hi16(gw.y));
;       u32x2 w; w.x = pk2(v0, v1); w.y = pk2(v2, v3); *(u32x2*)(op + d) = w;
;     }
.LBB0_1461:
	v_lshl_add_u64 v[2:3], v[172:173], 0, s[26:27]
	v_lshl_add_u64 v[6:7], v[2:3], 0, s[46:47]
	v_lshlrev_b32_e32 v0, 1, v118
	v_lshl_add_u64 v[10:11], v[6:7], 0, v[0:1]
	global_load_dwordx2 v[234:235], v[10:11], off
	global_load_dwordx2 v[236:237], v[10:11], off offset:16
	global_load_dwordx2 v[238:239], v[10:11], off offset:32
	global_load_dwordx2 v[240:241], v[10:11], off offset:48
	global_load_dwordx2 v[242:243], v[10:11], off offset:64
	global_load_dwordx2 v[244:245], v[10:11], off offset:80
	global_load_dwordx2 v[246:247], v[10:11], off offset:96
	global_load_dwordx2 v[248:249], v[10:11], off offset:112
	v_lshlrev_b32_e32 v2, 16, v219
	ds_bpermute_b32 v4, v218, v220
	v_mul_f32_e32 v2, 0xbfb8aa3b, v2
	v_exp_f32_e32 v5, v2
	ds_read2st64_b32 v[14:15], v193 offset0:160 offset1:161
	ds_read2st64_b32 v[48:49], v193 offset0:162 offset1:163
	ds_read2st64_b32 v[50:51], v193 offset0:164 offset1:165
	ds_read2st64_b32 v[52:53], v193 offset0:166 offset1:167
	v_lshlrev_b64 v[2:3], 9, v[170:171]
	s_waitcnt lgkmcnt(4)
	v_add_f32_e32 v4, v220, v4
	v_add_f32_e32 v5, 1.0, v5
	v_rcp_f32_e32 v4, v4
	v_rcp_f32_e32 v5, v5
	v_lshl_add_u64 v[2:3], s[30:31], 0, v[2:3]
	v_lshl_add_u64 v[8:9], v[2:3], 0, v[0:1]
	v_lshlrev_b32_e32 v0, 1, v120
	v_mul_f32_e32 v4, v5, v4
	v_lshl_add_u64 v[54:55], v[6:7], 0, v[0:1]
	s_waitcnt vmcnt(7)
	v_lshlrev_b32_e32 v56, 16, v234
	v_and_b32_e32 v57, 0xffff0000, v234
	v_lshlrev_b32_e32 v12, 16, v235
	v_and_b32_e32 v13, 0xffff0000, v235
	v_mul_f32_e32 v5, 0xbfb8aa3b, v56
	v_mul_f32_e32 v58, 0xbfb8aa3b, v57
	v_mul_f32_e32 v59, 0xbfb8aa3b, v12
	v_mul_f32_e32 v60, 0xbfb8aa3b, v13
	v_exp_f32_e32 v5, v5
	v_exp_f32_e32 v58, v58
	v_exp_f32_e32 v59, v59
	v_exp_f32_e32 v60, v60
	v_add_f32_e32 v5, 1.0, v5
	v_add_f32_e32 v61, 1.0, v58
	v_add_f32_e32 v62, 1.0, v59
	v_add_f32_e32 v63, 1.0, v60
	v_rcp_f32_e32 v58, v5
	v_rcp_f32_e32 v59, v61
	v_rcp_f32_e32 v60, v62
	v_rcp_f32_e32 v61, v63
	s_waitcnt lgkmcnt(3)
	v_pk_fma_f32 v[14:15], v[32:33], v[4:5], v[14:15] op_sel_hi:[1,0,1]
	s_waitcnt lgkmcnt(2)
	v_pk_fma_f32 v[32:33], v[34:35], v[4:5], v[48:49] op_sel_hi:[1,0,1]
	v_pk_mul_f32 v[34:35], v[58:59], v[56:57]
	v_pk_mul_f32 v[12:13], v[60:61], v[12:13]
	v_pk_mul_f32 v[14:15], v[14:15], v[34:35]
	v_pk_mul_f32 v[12:13], v[32:33], v[12:13]
	v_cvt_pk_bf16_f32 v14, v14, v15
	v_cvt_pk_bf16_f32 v15, v12, v13
	global_store_dwordx2 v[8:9], v[14:15], off
	v_lshl_add_u64 v[14:15], v[2:3], 0, v[0:1]
	v_lshlrev_b32_e32 v0, 1, v128
	v_lshl_add_u64 v[32:33], v[6:7], 0, v[0:1]
	s_waitcnt vmcnt(7)
	v_lshlrev_b32_e32 v34, 16, v236
	v_and_b32_e32 v35, 0xffff0000, v236
	v_lshlrev_b32_e32 v12, 16, v237
	v_and_b32_e32 v13, 0xffff0000, v237
	v_mul_f32_e32 v5, 0xbfb8aa3b, v34
	v_mul_f32_e32 v48, 0xbfb8aa3b, v35
	v_mul_f32_e32 v49, 0xbfb8aa3b, v12
	v_mul_f32_e32 v54, 0xbfb8aa3b, v13
	v_exp_f32_e32 v5, v5
	v_exp_f32_e32 v48, v48
	v_exp_f32_e32 v49, v49
	v_exp_f32_e32 v54, v54
	v_add_f32_e32 v5, 1.0, v5
	v_add_f32_e32 v55, 1.0, v48
	v_add_f32_e32 v56, 1.0, v49
	v_add_f32_e32 v57, 1.0, v54
	v_rcp_f32_e32 v48, v5
	v_rcp_f32_e32 v49, v55
	v_rcp_f32_e32 v54, v56
	v_rcp_f32_e32 v55, v57
	s_waitcnt lgkmcnt(1)
	v_pk_fma_f32 v[36:37], v[36:37], v[4:5], v[50:51] op_sel_hi:[1,0,1]
	s_waitcnt lgkmcnt(0)
	v_pk_fma_f32 v[38:39], v[38:39], v[4:5], v[52:53] op_sel_hi:[1,0,1]
	v_pk_mul_f32 v[34:35], v[48:49], v[34:35]
	v_pk_mul_f32 v[12:13], v[54:55], v[12:13]
	v_pk_mul_f32 v[34:35], v[36:37], v[34:35]
	v_pk_mul_f32 v[12:13], v[38:39], v[12:13]
	v_cvt_pk_bf16_f32 v34, v34, v35
	v_cvt_pk_bf16_f32 v35, v12, v13
	global_store_dwordx2 v[14:15], v[34:35], off
	ds_read2st64_b32 v[14:15], v193 offset0:168 offset1:169
	ds_read2st64_b32 v[32:33], v193 offset0:170 offset1:171
	ds_read2st64_b32 v[34:35], v193 offset0:172 offset1:173
	ds_read2st64_b32 v[36:37], v193 offset0:174 offset1:175
	v_lshl_add_u64 v[38:39], v[2:3], 0, v[0:1]
	v_lshlrev_b32_e32 v0, 1, v136
	v_lshl_add_u64 v[48:49], v[6:7], 0, v[0:1]
	s_waitcnt vmcnt(7)
	v_lshlrev_b32_e32 v50, 16, v238
	v_and_b32_e32 v51, 0xffff0000, v238
	v_lshlrev_b32_e32 v12, 16, v239
	v_and_b32_e32 v13, 0xffff0000, v239
	v_mul_f32_e32 v5, 0xbfb8aa3b, v50
	v_mul_f32_e32 v52, 0xbfb8aa3b, v51
	v_mul_f32_e32 v53, 0xbfb8aa3b, v12
	v_mul_f32_e32 v54, 0xbfb8aa3b, v13
	v_exp_f32_e32 v5, v5
	v_exp_f32_e32 v52, v52
	v_exp_f32_e32 v53, v53
	v_exp_f32_e32 v54, v54
	v_add_f32_e32 v5, 1.0, v5
	v_add_f32_e32 v55, 1.0, v52
	v_add_f32_e32 v56, 1.0, v53
	v_add_f32_e32 v57, 1.0, v54
	v_rcp_f32_e32 v52, v5
	v_rcp_f32_e32 v53, v55
	v_rcp_f32_e32 v54, v56
	v_rcp_f32_e32 v55, v57
	s_waitcnt lgkmcnt(3)
	v_pk_fma_f32 v[14:15], v[40:41], v[4:5], v[14:15] op_sel_hi:[1,0,1]
	s_waitcnt lgkmcnt(2)
	v_pk_fma_f32 v[32:33], v[42:43], v[4:5], v[32:33] op_sel_hi:[1,0,1]
	v_pk_mul_f32 v[40:41], v[52:53], v[50:51]
	v_pk_mul_f32 v[12:13], v[54:55], v[12:13]
	v_pk_mul_f32 v[14:15], v[14:15], v[40:41]
	v_pk_mul_f32 v[12:13], v[32:33], v[12:13]
	v_cvt_pk_bf16_f32 v14, v14, v15
	v_cvt_pk_bf16_f32 v15, v12, v13
	global_store_dwordx2 v[38:39], v[14:15], off
	v_lshl_add_u64 v[14:15], v[2:3], 0, v[0:1]
	s_waitcnt vmcnt(7)
	v_lshlrev_b32_e32 v32, 16, v240
	v_and_b32_e32 v33, 0xffff0000, v240
	v_lshlrev_b32_e32 v12, 16, v241
	v_and_b32_e32 v13, 0xffff0000, v241
	v_mul_f32_e32 v0, 0xbfb8aa3b, v32
	v_mul_f32_e32 v5, 0xbfb8aa3b, v33
	v_mul_f32_e32 v38, 0xbfb8aa3b, v12
	v_mul_f32_e32 v39, 0xbfb8aa3b, v13
	v_exp_f32_e32 v0, v0
	v_exp_f32_e32 v5, v5
	v_exp_f32_e32 v38, v38
	v_exp_f32_e32 v39, v39
	v_add_f32_e32 v0, 1.0, v0
	v_add_f32_e32 v5, 1.0, v5
	v_add_f32_e32 v40, 1.0, v38
	v_add_f32_e32 v41, 1.0, v39
	v_rcp_f32_e32 v38, v0
	v_rcp_f32_e32 v39, v5
	v_rcp_f32_e32 v40, v40
	v_rcp_f32_e32 v41, v41
	s_waitcnt lgkmcnt(1)
; __device__ __forceinline__ unsigned pk2(float lo, float hi) { f32x2_t v = {lo, hi}; bf16x2_t b = __builtin_convertvector(v, bf16x2_t); return __builtin_bit_cast(unsigned, b); }
; __device__ __forceinline__ float lo16(unsigned w) { return __uint_as_float(w << 16); }
; __device__ __forceinline__ float hi16(unsigned w) { return __uint_as_float(w & 0xffff0000u); }
; __device__ __forceinline__ float frcp(float x) { return __builtin_amdgcn_rcpf(x); }
; __device__ __forceinline__ float siluf_(float x) { return x * sigmoidf_(x); }
; __device__ __forceinline__ float merge_l(float l) { return l + __shfl_xor(l, 32); }
; __device__ __forceinline__ void nsa_unit(int b, int qt, const bf16_t* proj, const bf16_t* vt, const bf16_t* kc, const bf16_t* vcT, bf16_t* ab0, LAS unsigned char* lds, int tid, int wid, int lane) {
;     ...
;     const float sc = g2 * frcp(merge_l(st.l));
; #pragma unroll
;     for (int r = 0; r < 16; ++r) { ot[0][r] = stash[r * 64] + sc * st.o[0][r]; ot[1][r] = stash[(16 + r) * 64] + sc * st.o[1][r]; }
;   }
;   const bf16_t* gp = proj + tok * NP + C_GATE + head * 64;
;   bf16_t* op = ab0 + tok * 256 + head * 64;
; #pragma unroll
;   for (int dh = 0; dh < 2; ++dh)
; #pragma unroll
;     for (int g = 0; g < 4; ++g) {
;       const int d = 32 * dh + 8 * g + 4 * hi;
;       const u32x2 gw = *(const u32x2*)(gp + d);
;       const float v0 = ot[dh][4 * g] * siluf_(lo16(gw.x)), v1 = ot[dh][4 * g + 1] * siluf_(hi16(gw.x));
;       const float v2 = ot[dh][4 * g + 2] * siluf_(lo16(gw.y)), v3 = ot[dh][4 * g + 3] * siluf_(hi16(gw.y));
;       u32x2 w; w.x = pk2(v0, v1); w.y = pk2(v2, v3); *(u32x2*)(op + d) = w;
;     }
	v_pk_fma_f32 v[34:35], v[44:45], v[4:5], v[34:35] op_sel_hi:[1,0,1]
	s_waitcnt lgkmcnt(0)
	v_pk_fma_f32 v[36:37], v[46:47], v[4:5], v[36:37] op_sel_hi:[1,0,1]
	v_pk_mul_f32 v[32:33], v[38:39], v[32:33]
	v_pk_mul_f32 v[12:13], v[40:41], v[12:13]
	v_pk_mul_f32 v[32:33], v[34:35], v[32:33]
	v_pk_mul_f32 v[12:13], v[36:37], v[12:13]
	v_cvt_pk_bf16_f32 v32, v32, v33
	v_cvt_pk_bf16_f32 v33, v12, v13
	global_store_dwordx2 v[14:15], v[32:33], off
	ds_read2st64_b32 v[12:13], v193 offset0:176 offset1:177
	ds_read2st64_b32 v[14:15], v193 offset0:178 offset1:179
	ds_read2st64_b32 v[32:33], v193 offset0:180 offset1:181
	ds_read2st64_b32 v[34:35], v193 offset0:182 offset1:183
	v_lshlrev_b32_e32 v0, 1, v122
	v_lshl_add_u64 v[36:37], v[6:7], 0, v[0:1]
	s_waitcnt vmcnt(7)
	v_lshlrev_b32_e32 v38, 16, v242
	v_and_b32_e32 v39, 0xffff0000, v242
	v_lshlrev_b32_e32 v10, 16, v243
	v_and_b32_e32 v11, 0xffff0000, v243
	v_mul_f32_e32 v5, 0xbfb8aa3b, v38
	v_mul_f32_e32 v40, 0xbfb8aa3b, v39
	v_mul_f32_e32 v41, 0xbfb8aa3b, v10
	v_mul_f32_e32 v42, 0xbfb8aa3b, v11
	v_exp_f32_e32 v5, v5
	v_exp_f32_e32 v40, v40
	v_exp_f32_e32 v41, v41
	v_exp_f32_e32 v42, v42
	v_add_f32_e32 v5, 1.0, v5
	v_add_f32_e32 v43, 1.0, v40
	v_add_f32_e32 v44, 1.0, v41
	v_add_f32_e32 v45, 1.0, v42
	v_rcp_f32_e32 v40, v5
	v_rcp_f32_e32 v41, v43
	v_rcp_f32_e32 v42, v44
	v_rcp_f32_e32 v43, v45
	s_waitcnt lgkmcnt(3)
	v_pk_fma_f32 v[12:13], v[16:17], v[4:5], v[12:13] op_sel_hi:[1,0,1]
	s_waitcnt lgkmcnt(2)
	v_pk_fma_f32 v[14:15], v[18:19], v[4:5], v[14:15] op_sel_hi:[1,0,1]
	v_pk_mul_f32 v[16:17], v[40:41], v[38:39]
	v_pk_mul_f32 v[10:11], v[42:43], v[10:11]
	v_pk_mul_f32 v[12:13], v[12:13], v[16:17]
	v_pk_mul_f32 v[10:11], v[14:15], v[10:11]
	v_cvt_pk_bf16_f32 v12, v12, v13
	v_cvt_pk_bf16_f32 v13, v10, v11
	global_store_dwordx2 v[8:9], v[12:13], off offset:64
	v_lshl_add_u64 v[10:11], v[2:3], 0, v[0:1]
	v_lshlrev_b32_e32 v0, 1, v130
	v_lshl_add_u64 v[12:13], v[6:7], 0, v[0:1]
	s_waitcnt vmcnt(7)
	v_lshlrev_b32_e32 v14, 16, v244
	v_and_b32_e32 v15, 0xffff0000, v244
	v_lshlrev_b32_e32 v8, 16, v245
	v_and_b32_e32 v9, 0xffff0000, v245
	v_mul_f32_e32 v5, 0xbfb8aa3b, v14
	v_mul_f32_e32 v16, 0xbfb8aa3b, v15
	v_mul_f32_e32 v17, 0xbfb8aa3b, v8
	v_mul_f32_e32 v18, 0xbfb8aa3b, v9
	v_exp_f32_e32 v5, v5
	v_exp_f32_e32 v16, v16
	v_exp_f32_e32 v17, v17
	v_exp_f32_e32 v18, v18
	v_add_f32_e32 v5, 1.0, v5
	v_add_f32_e32 v19, 1.0, v16
	v_add_f32_e32 v36, 1.0, v17
	v_add_f32_e32 v37, 1.0, v18
	v_rcp_f32_e32 v16, v5
	v_rcp_f32_e32 v17, v19
	v_rcp_f32_e32 v18, v36
	v_rcp_f32_e32 v19, v37
	s_waitcnt lgkmcnt(1)
	v_pk_fma_f32 v[20:21], v[20:21], v[4:5], v[32:33] op_sel_hi:[1,0,1]
	s_waitcnt lgkmcnt(0)
	v_pk_fma_f32 v[22:23], v[22:23], v[4:5], v[34:35] op_sel_hi:[1,0,1]
	v_pk_mul_f32 v[14:15], v[16:17], v[14:15]
	v_pk_mul_f32 v[8:9], v[18:19], v[8:9]
	v_pk_mul_f32 v[14:15], v[20:21], v[14:15]
	v_pk_mul_f32 v[8:9], v[22:23], v[8:9]
	v_cvt_pk_bf16_f32 v14, v14, v15
	v_cvt_pk_bf16_f32 v15, v8, v9
	global_store_dwordx2 v[10:11], v[14:15], off
	ds_read2st64_b32 v[10:11], v193 offset0:184 offset1:185
	ds_read2st64_b32 v[12:13], v193 offset0:186 offset1:187
	ds_read2st64_b32 v[14:15], v193 offset0:188 offset1:189
	ds_read2st64_b32 v[16:17], v193 offset0:190 offset1:191
	v_lshl_add_u64 v[18:19], v[2:3], 0, v[0:1]
	v_lshlrev_b32_e32 v0, 1, v138
	v_lshl_add_u64 v[6:7], v[6:7], 0, v[0:1]
	v_lshl_add_u64 v[2:3], v[2:3], 0, v[0:1]
	s_waitcnt vmcnt(7)
	v_lshlrev_b32_e32 v20, 16, v246
	v_and_b32_e32 v21, 0xffff0000, v246
	v_lshlrev_b32_e32 v8, 16, v247
	v_and_b32_e32 v9, 0xffff0000, v247
	v_mul_f32_e32 v5, 0xbfb8aa3b, v20
	v_mul_f32_e32 v22, 0xbfb8aa3b, v21
	v_mul_f32_e32 v23, 0xbfb8aa3b, v8
	v_mul_f32_e32 v32, 0xbfb8aa3b, v9
	v_exp_f32_e32 v5, v5
	v_exp_f32_e32 v22, v22
	v_exp_f32_e32 v23, v23
	v_exp_f32_e32 v32, v32
	v_add_f32_e32 v5, 1.0, v5
	v_add_f32_e32 v33, 1.0, v22
	v_add_f32_e32 v34, 1.0, v23
	v_add_f32_e32 v35, 1.0, v32
	v_rcp_f32_e32 v22, v5
	v_rcp_f32_e32 v23, v33
	v_rcp_f32_e32 v32, v34
	v_rcp_f32_e32 v33, v35
	s_waitcnt lgkmcnt(3)
	v_pk_fma_f32 v[10:11], v[24:25], v[4:5], v[10:11] op_sel_hi:[1,0,1]
	s_waitcnt lgkmcnt(2)
	v_pk_fma_f32 v[12:13], v[26:27], v[4:5], v[12:13] op_sel_hi:[1,0,1]
	v_pk_mul_f32 v[20:21], v[22:23], v[20:21]
	v_pk_mul_f32 v[8:9], v[32:33], v[8:9]
	v_pk_mul_f32 v[10:11], v[10:11], v[20:21]
	v_pk_mul_f32 v[8:9], v[12:13], v[8:9]
	v_cvt_pk_bf16_f32 v10, v10, v11
	v_cvt_pk_bf16_f32 v11, v8, v9
	global_store_dwordx2 v[18:19], v[10:11], off
	s_waitcnt vmcnt(7)
	v_lshlrev_b32_e32 v8, 16, v248
	v_and_b32_e32 v9, 0xffff0000, v248
	v_lshlrev_b32_e32 v6, 16, v249
	v_and_b32_e32 v7, 0xffff0000, v249
	v_mul_f32_e32 v0, 0xbfb8aa3b, v8
	v_mul_f32_e32 v5, 0xbfb8aa3b, v9
	v_mul_f32_e32 v10, 0xbfb8aa3b, v6
	v_mul_f32_e32 v11, 0xbfb8aa3b, v7
	v_exp_f32_e32 v0, v0
	v_exp_f32_e32 v5, v5
	v_exp_f32_e32 v10, v10
	v_exp_f32_e32 v11, v11
	v_add_f32_e32 v0, 1.0, v0
	v_add_f32_e32 v5, 1.0, v5
	v_add_f32_e32 v12, 1.0, v10
	v_add_f32_e32 v13, 1.0, v11
	v_rcp_f32_e32 v10, v0
	v_rcp_f32_e32 v11, v5
	v_rcp_f32_e32 v12, v12
	v_rcp_f32_e32 v13, v13
	s_waitcnt lgkmcnt(1)
	v_pk_fma_f32 v[14:15], v[28:29], v[4:5], v[14:15] op_sel_hi:[1,0,1]
	s_waitcnt lgkmcnt(0)
	v_pk_fma_f32 v[4:5], v[30:31], v[4:5], v[16:17] op_sel_hi:[1,0,1]
	v_pk_mul_f32 v[8:9], v[10:11], v[8:9]
	v_pk_mul_f32 v[6:7], v[12:13], v[6:7]
	v_pk_mul_f32 v[8:9], v[14:15], v[8:9]
	v_pk_mul_f32 v[4:5], v[4:5], v[6:7]
	v_cvt_pk_bf16_f32 v6, v8, v9
	v_cvt_pk_bf16_f32 v7, v4, v5
	global_store_dwordx2 v[2:3], v[6:7], off
	s_barrier

; __device__ __forceinline__ unsigned pk2(float lo, float hi) { f32x2_t v = {lo, hi}; bf16x2_t b = __builtin_convertvector(v, bf16x2_t); return __builtin_bit_cast(unsigned, b); }
; __device__ __forceinline__ float lo16(unsigned w) { return __uint_as_float(w << 16); }
; __device__ __forceinline__ float hi16(unsigned w) { return __uint_as_float(w & 0xffff0000u); }
; __device__ __forceinline__ float frcp(float x) { return __builtin_amdgcn_rcpf(x); }
; __device__ __forceinline__ float siluf_(float x) { return x * sigmoidf_(x); }
; __device__ __forceinline__ float merge_l(float l) { return l + __shfl_xor(l, 32); }
; __device__ __forceinline__ void fox_unit(int b, int h, int qt, const bf16_t* proj, const bf16_t* vt, const float* c2, const float* kn, bf16_t* ab3, LAS unsigned char* lds, int tid, int wid, int lane) {
;     ...
;   const float inv = frcp(merge_l(st.l));
;   const bf16_t* gp = proj + tok * NP + C_GATE + 768 + h * 64;
;   bf16_t* op = ab3 + tok * 256 + h * 64;
; #pragma unroll
;   for (int dh = 0; dh < 2; ++dh)
; #pragma unroll
;     for (int g = 0; g < 4; ++g) {
;       const int d = 32 * dh + 8 * g + 4 * hi;
;       const u32x2 gw = *(const u32x2*)(gp + d);
;       const float v0 = st.o[dh][4 * g] * inv * siluf_(lo16(gw.x)), v1 = st.o[dh][4 * g + 1] * inv * siluf_(hi16(gw.x));
;       const float v2 = st.o[dh][4 * g + 2] * inv * siluf_(lo16(gw.y)), v3 = st.o[dh][4 * g + 3] * inv * siluf_(hi16(gw.y));
;       u32x2 w; w.x = pk2(v0, v1); w.y = pk2(v2, v3); *(u32x2*)(op + d) = w;
;     }
.LBB0_1498:
	s_mov_b32 s1, s27
	v_lshl_add_u64 v[2:3], v[172:173], 0, s[0:1]
	v_lshl_add_u64 v[6:7], v[2:3], 0, s[36:37]
	v_lshlrev_b32_e32 v0, 1, v118
	v_lshl_add_u64 v[10:11], v[6:7], 0, v[0:1]
	global_load_dwordx2 v[234:235], v[10:11], off
	global_load_dwordx2 v[236:237], v[10:11], off offset:16
	global_load_dwordx2 v[238:239], v[10:11], off offset:32
	global_load_dwordx2 v[240:241], v[10:11], off offset:48
	global_load_dwordx2 v[242:243], v[10:11], off offset:64
	global_load_dwordx2 v[244:245], v[10:11], off offset:80
	global_load_dwordx2 v[246:247], v[10:11], off offset:96
	global_load_dwordx2 v[248:249], v[10:11], off offset:112
	ds_bpermute_b32 v4, v175, v219
	v_lshlrev_b64 v[2:3], 9, v[170:171]
	v_lshl_add_u64 v[2:3], s[28:29], 0, v[2:3]
	v_lshl_add_u64 v[2:3], v[2:3], 0, s[0:1]
	v_lshl_add_u64 v[8:9], v[2:3], 0, v[0:1]
	s_waitcnt lgkmcnt(0)
	v_add_f32_e32 v4, v219, v4
	v_rcp_f32_e32 v4, v4
	v_lshlrev_b32_e32 v0, 1, v120
	v_lshl_add_u64 v[14:15], v[6:7], 0, v[0:1]
	s_mov_b64 s[0:1], 0
	s_waitcnt vmcnt(7)
	v_lshlrev_b32_e32 v48, 16, v234
	v_and_b32_e32 v49, 0xffff0000, v234
	v_lshlrev_b32_e32 v12, 16, v235
	v_and_b32_e32 v13, 0xffff0000, v235
	v_mul_f32_e32 v5, 0xbfb8aa3b, v48
	v_mul_f32_e32 v50, 0xbfb8aa3b, v49
	v_mul_f32_e32 v51, 0xbfb8aa3b, v12
	v_mul_f32_e32 v52, 0xbfb8aa3b, v13
	v_exp_f32_e32 v5, v5
	v_exp_f32_e32 v50, v50
	v_exp_f32_e32 v51, v51
	v_exp_f32_e32 v52, v52
	v_add_f32_e32 v5, 1.0, v5
	v_add_f32_e32 v53, 1.0, v50
	v_add_f32_e32 v54, 1.0, v51
	v_add_f32_e32 v55, 1.0, v52
	v_rcp_f32_e32 v50, v5
	v_rcp_f32_e32 v51, v53
	v_rcp_f32_e32 v52, v54
	v_rcp_f32_e32 v53, v55
	v_pk_mul_f32 v[32:33], v[32:33], v[4:5] op_sel_hi:[1,0]
	v_pk_mul_f32 v[34:35], v[34:35], v[4:5] op_sel_hi:[1,0]
	v_pk_mul_f32 v[48:49], v[50:51], v[48:49]
	v_pk_mul_f32 v[12:13], v[52:53], v[12:13]
	v_pk_mul_f32 v[32:33], v[32:33], v[48:49]
	v_pk_mul_f32 v[12:13], v[34:35], v[12:13]
	v_cvt_pk_bf16_f32 v32, v32, v33
	v_cvt_pk_bf16_f32 v33, v12, v13
	global_store_dwordx2 v[8:9], v[32:33], off
	v_lshl_add_u64 v[14:15], v[2:3], 0, v[0:1]
	v_lshlrev_b32_e32 v0, 1, v128
	v_lshl_add_u64 v[32:33], v[6:7], 0, v[0:1]
	s_waitcnt vmcnt(7)
	v_lshlrev_b32_e32 v34, 16, v236
	v_and_b32_e32 v35, 0xffff0000, v236
	v_lshlrev_b32_e32 v12, 16, v237
	v_and_b32_e32 v13, 0xffff0000, v237
	v_mul_f32_e32 v5, 0xbfb8aa3b, v34
	v_mul_f32_e32 v48, 0xbfb8aa3b, v35
	v_mul_f32_e32 v49, 0xbfb8aa3b, v12
	v_mul_f32_e32 v50, 0xbfb8aa3b, v13
	v_exp_f32_e32 v5, v5
	v_exp_f32_e32 v48, v48
	v_exp_f32_e32 v49, v49
	v_exp_f32_e32 v50, v50
	v_add_f32_e32 v5, 1.0, v5
	v_add_f32_e32 v51, 1.0, v48
	v_add_f32_e32 v52, 1.0, v49
	v_add_f32_e32 v53, 1.0, v50
	v_rcp_f32_e32 v48, v5
	v_rcp_f32_e32 v49, v51
	v_rcp_f32_e32 v50, v52
	v_rcp_f32_e32 v51, v53
	v_pk_mul_f32 v[36:37], v[36:37], v[4:5] op_sel_hi:[1,0]
	v_pk_mul_f32 v[38:39], v[38:39], v[4:5] op_sel_hi:[1,0]
	v_pk_mul_f32 v[34:35], v[48:49], v[34:35]
	v_pk_mul_f32 v[12:13], v[50:51], v[12:13]
	v_pk_mul_f32 v[34:35], v[36:37], v[34:35]
	v_pk_mul_f32 v[12:13], v[38:39], v[12:13]
	v_cvt_pk_bf16_f32 v34, v34, v35
	v_cvt_pk_bf16_f32 v35, v12, v13
	global_store_dwordx2 v[14:15], v[34:35], off
	v_lshl_add_u64 v[14:15], v[2:3], 0, v[0:1]
	v_lshlrev_b32_e32 v0, 1, v136
	v_lshl_add_u64 v[32:33], v[6:7], 0, v[0:1]
	s_waitcnt vmcnt(7)
	v_lshlrev_b32_e32 v34, 16, v238
	v_and_b32_e32 v35, 0xffff0000, v238
	v_lshlrev_b32_e32 v12, 16, v239
	v_and_b32_e32 v13, 0xffff0000, v239
	v_mul_f32_e32 v5, 0xbfb8aa3b, v34
	v_mul_f32_e32 v36, 0xbfb8aa3b, v35
	v_mul_f32_e32 v37, 0xbfb8aa3b, v12
	v_mul_f32_e32 v38, 0xbfb8aa3b, v13
	v_exp_f32_e32 v5, v5
	v_exp_f32_e32 v36, v36
	v_exp_f32_e32 v37, v37
	v_exp_f32_e32 v38, v38
	v_add_f32_e32 v5, 1.0, v5
	v_add_f32_e32 v39, 1.0, v36
	v_add_f32_e32 v48, 1.0, v37
	v_add_f32_e32 v49, 1.0, v38
	v_rcp_f32_e32 v36, v5
	v_rcp_f32_e32 v37, v39
	v_rcp_f32_e32 v38, v48
	v_rcp_f32_e32 v39, v49
	v_pk_mul_f32 v[40:41], v[40:41], v[4:5] op_sel_hi:[1,0]
	v_pk_mul_f32 v[42:43], v[42:43], v[4:5] op_sel_hi:[1,0]
	v_pk_mul_f32 v[34:35], v[36:37], v[34:35]
	v_pk_mul_f32 v[12:13], v[38:39], v[12:13]
	v_pk_mul_f32 v[34:35], v[40:41], v[34:35]
	v_pk_mul_f32 v[12:13], v[42:43], v[12:13]
	v_cvt_pk_bf16_f32 v34, v34, v35
	v_cvt_pk_bf16_f32 v35, v12, v13
	global_store_dwordx2 v[14:15], v[34:35], off
	v_lshl_add_u64 v[14:15], v[2:3], 0, v[0:1]
	s_waitcnt vmcnt(7)
; __device__ __forceinline__ unsigned pk2(float lo, float hi) { f32x2_t v = {lo, hi}; bf16x2_t b = __builtin_convertvector(v, bf16x2_t); return __builtin_bit_cast(unsigned, b); }
; __device__ __forceinline__ float lo16(unsigned w) { return __uint_as_float(w << 16); }
; __device__ __forceinline__ float hi16(unsigned w) { return __uint_as_float(w & 0xffff0000u); }
; __device__ __forceinline__ float frcp(float x) { return __builtin_amdgcn_rcpf(x); }
; __device__ __forceinline__ float siluf_(float x) { return x * sigmoidf_(x); }
; __device__ __forceinline__ float merge_l(float l) { return l + __shfl_xor(l, 32); }
; __device__ __forceinline__ void fox_unit(int b, int h, int qt, const bf16_t* proj, const bf16_t* vt, const float* c2, const float* kn, bf16_t* ab3, LAS unsigned char* lds, int tid, int wid, int lane) {
;     ...
;   const float inv = frcp(merge_l(st.l));
;   const bf16_t* gp = proj + tok * NP + C_GATE + 768 + h * 64;
;   bf16_t* op = ab3 + tok * 256 + h * 64;
; #pragma unroll
;   for (int dh = 0; dh < 2; ++dh)
; #pragma unroll
;     for (int g = 0; g < 4; ++g) {
;       const int d = 32 * dh + 8 * g + 4 * hi;
;       const u32x2 gw = *(const u32x2*)(gp + d);
;       const float v0 = st.o[dh][4 * g] * inv * siluf_(lo16(gw.x)), v1 = st.o[dh][4 * g + 1] * inv * siluf_(hi16(gw.x));
;       const float v2 = st.o[dh][4 * g + 2] * inv * siluf_(lo16(gw.y)), v3 = st.o[dh][4 * g + 3] * inv * siluf_(hi16(gw.y));
;       u32x2 w; w.x = pk2(v0, v1); w.y = pk2(v2, v3); *(u32x2*)(op + d) = w;
;     }
	v_lshlrev_b32_e32 v32, 16, v240
	v_and_b32_e32 v33, 0xffff0000, v240
	v_lshlrev_b32_e32 v12, 16, v241
	v_and_b32_e32 v13, 0xffff0000, v241
	v_mul_f32_e32 v0, 0xbfb8aa3b, v32
	v_mul_f32_e32 v5, 0xbfb8aa3b, v33
	v_mul_f32_e32 v34, 0xbfb8aa3b, v12
	v_mul_f32_e32 v35, 0xbfb8aa3b, v13
	v_exp_f32_e32 v0, v0
	v_exp_f32_e32 v5, v5
	v_exp_f32_e32 v34, v34
	v_exp_f32_e32 v35, v35
	v_add_f32_e32 v0, 1.0, v0
	v_add_f32_e32 v5, 1.0, v5
	v_add_f32_e32 v36, 1.0, v34
	v_add_f32_e32 v37, 1.0, v35
	v_rcp_f32_e32 v34, v0
	v_rcp_f32_e32 v35, v5
	v_rcp_f32_e32 v36, v36
	v_rcp_f32_e32 v37, v37
	v_pk_mul_f32 v[38:39], v[44:45], v[4:5] op_sel_hi:[1,0]
	v_pk_mul_f32 v[40:41], v[46:47], v[4:5] op_sel_hi:[1,0]
	v_pk_mul_f32 v[32:33], v[34:35], v[32:33]
	v_pk_mul_f32 v[12:13], v[36:37], v[12:13]
	v_pk_mul_f32 v[32:33], v[38:39], v[32:33]
	v_pk_mul_f32 v[12:13], v[40:41], v[12:13]
	v_cvt_pk_bf16_f32 v32, v32, v33
	v_cvt_pk_bf16_f32 v33, v12, v13
	global_store_dwordx2 v[14:15], v[32:33], off
	v_lshlrev_b32_e32 v0, 1, v122
	v_lshl_add_u64 v[12:13], v[6:7], 0, v[0:1]
	s_waitcnt vmcnt(7)
	v_lshlrev_b32_e32 v14, 16, v242
	v_and_b32_e32 v15, 0xffff0000, v242
	v_lshlrev_b32_e32 v10, 16, v243
	v_and_b32_e32 v11, 0xffff0000, v243
	v_mul_f32_e32 v5, 0xbfb8aa3b, v14
	v_mul_f32_e32 v32, 0xbfb8aa3b, v15
	v_mul_f32_e32 v33, 0xbfb8aa3b, v10
	v_mul_f32_e32 v34, 0xbfb8aa3b, v11
	v_exp_f32_e32 v5, v5
	v_exp_f32_e32 v32, v32
	v_exp_f32_e32 v33, v33
	v_exp_f32_e32 v34, v34
	v_add_f32_e32 v5, 1.0, v5
	v_add_f32_e32 v35, 1.0, v32
	v_add_f32_e32 v36, 1.0, v33
	v_add_f32_e32 v37, 1.0, v34
	v_rcp_f32_e32 v32, v5
	v_rcp_f32_e32 v33, v35
	v_rcp_f32_e32 v34, v36
	v_rcp_f32_e32 v35, v37
	v_pk_mul_f32 v[16:17], v[16:17], v[4:5] op_sel_hi:[1,0]
	v_pk_mul_f32 v[18:19], v[18:19], v[4:5] op_sel_hi:[1,0]
	v_pk_mul_f32 v[14:15], v[32:33], v[14:15]
	v_pk_mul_f32 v[10:11], v[34:35], v[10:11]
	v_pk_mul_f32 v[14:15], v[16:17], v[14:15]
	v_pk_mul_f32 v[10:11], v[18:19], v[10:11]
	v_cvt_pk_bf16_f32 v14, v14, v15
	v_cvt_pk_bf16_f32 v15, v10, v11
	global_store_dwordx2 v[8:9], v[14:15], off offset:64
	v_lshl_add_u64 v[10:11], v[2:3], 0, v[0:1]
	v_lshlrev_b32_e32 v0, 1, v130
	v_lshl_add_u64 v[12:13], v[6:7], 0, v[0:1]
	s_waitcnt vmcnt(7)
	v_lshlrev_b32_e32 v14, 16, v244
	v_and_b32_e32 v15, 0xffff0000, v244
	v_lshlrev_b32_e32 v8, 16, v245
	v_and_b32_e32 v9, 0xffff0000, v245
	v_mul_f32_e32 v5, 0xbfb8aa3b, v14
	v_mul_f32_e32 v16, 0xbfb8aa3b, v15
	v_mul_f32_e32 v17, 0xbfb8aa3b, v8
	v_mul_f32_e32 v18, 0xbfb8aa3b, v9
	v_exp_f32_e32 v5, v5
	v_exp_f32_e32 v16, v16
	v_exp_f32_e32 v17, v17
	v_exp_f32_e32 v18, v18
	v_add_f32_e32 v5, 1.0, v5
	v_add_f32_e32 v19, 1.0, v16
	v_add_f32_e32 v32, 1.0, v17
	v_add_f32_e32 v33, 1.0, v18
	v_rcp_f32_e32 v16, v5
	v_rcp_f32_e32 v17, v19
	v_rcp_f32_e32 v18, v32
	v_rcp_f32_e32 v19, v33
	v_pk_mul_f32 v[20:21], v[20:21], v[4:5] op_sel_hi:[1,0]
	v_pk_mul_f32 v[22:23], v[22:23], v[4:5] op_sel_hi:[1,0]
	v_pk_mul_f32 v[14:15], v[16:17], v[14:15]
	v_pk_mul_f32 v[8:9], v[18:19], v[8:9]
	v_pk_mul_f32 v[14:15], v[20:21], v[14:15]
	v_pk_mul_f32 v[8:9], v[22:23], v[8:9]
	v_cvt_pk_bf16_f32 v14, v14, v15
	v_cvt_pk_bf16_f32 v15, v8, v9
	global_store_dwordx2 v[10:11], v[14:15], off
	v_lshl_add_u64 v[10:11], v[2:3], 0, v[0:1]
	v_lshlrev_b32_e32 v0, 1, v138
	v_lshl_add_u64 v[6:7], v[6:7], 0, v[0:1]
	v_lshl_add_u64 v[2:3], v[2:3], 0, v[0:1]
	s_waitcnt vmcnt(7)
	v_lshlrev_b32_e32 v12, 16, v246
	v_and_b32_e32 v13, 0xffff0000, v246
	v_lshlrev_b32_e32 v8, 16, v247
	v_and_b32_e32 v9, 0xffff0000, v247
	v_mul_f32_e32 v5, 0xbfb8aa3b, v12
	v_mul_f32_e32 v14, 0xbfb8aa3b, v13
	v_mul_f32_e32 v15, 0xbfb8aa3b, v8
	v_mul_f32_e32 v16, 0xbfb8aa3b, v9
	v_exp_f32_e32 v5, v5
	v_exp_f32_e32 v14, v14
	v_exp_f32_e32 v15, v15
	v_exp_f32_e32 v16, v16
	v_add_f32_e32 v5, 1.0, v5
	v_add_f32_e32 v17, 1.0, v14
	v_add_f32_e32 v18, 1.0, v15
	v_add_f32_e32 v19, 1.0, v16
	v_rcp_f32_e32 v14, v5
	v_rcp_f32_e32 v15, v17
	v_rcp_f32_e32 v16, v18
	v_rcp_f32_e32 v17, v19
	v_pk_mul_f32 v[18:19], v[24:25], v[4:5] op_sel_hi:[1,0]
	v_pk_mul_f32 v[20:21], v[26:27], v[4:5] op_sel_hi:[1,0]
	v_pk_mul_f32 v[12:13], v[14:15], v[12:13]
	v_pk_mul_f32 v[8:9], v[16:17], v[8:9]
	v_pk_mul_f32 v[12:13], v[18:19], v[12:13]
	v_pk_mul_f32 v[8:9], v[20:21], v[8:9]
	v_cvt_pk_bf16_f32 v12, v12, v13
	v_cvt_pk_bf16_f32 v13, v8, v9
	global_store_dwordx2 v[10:11], v[12:13], off
	s_waitcnt vmcnt(7)
	v_lshlrev_b32_e32 v8, 16, v248
	v_and_b32_e32 v9, 0xffff0000, v248
	v_lshlrev_b32_e32 v6, 16, v249
	v_and_b32_e32 v7, 0xffff0000, v249
	v_mul_f32_e32 v0, 0xbfb8aa3b, v8
	v_mul_f32_e32 v5, 0xbfb8aa3b, v9
	v_mul_f32_e32 v10, 0xbfb8aa3b, v6
	v_mul_f32_e32 v11, 0xbfb8aa3b, v7
	v_exp_f32_e32 v0, v0
	v_exp_f32_e32 v5, v5
	v_exp_f32_e32 v10, v10
	v_exp_f32_e32 v11, v11
	v_add_f32_e32 v0, 1.0, v0
	v_add_f32_e32 v5, 1.0, v5
	v_add_f32_e32 v12, 1.0, v10
	v_add_f32_e32 v13, 1.0, v11
	v_rcp_f32_e32 v10, v0
	v_rcp_f32_e32 v11, v5
	v_rcp_f32_e32 v12, v12
	v_rcp_f32_e32 v13, v13
	v_pk_mul_f32 v[14:15], v[28:29], v[4:5] op_sel_hi:[1,0]
	v_pk_mul_f32 v[4:5], v[30:31], v[4:5] op_sel_hi:[1,0]
	v_pk_mul_f32 v[8:9], v[10:11], v[8:9]
	v_pk_mul_f32 v[6:7], v[12:13], v[6:7]
	v_pk_mul_f32 v[8:9], v[14:15], v[8:9]
	v_pk_mul_f32 v[4:5], v[4:5], v[6:7]
	v_cvt_pk_bf16_f32 v6, v8, v9
	v_cvt_pk_bf16_f32 v7, v4, v5
	global_store_dwordx2 v[2:3], v[6:7], off
